# baseline (speedup 1.0000x reference)
; template <int MODE>
; DEV void gemm_phase(const bf16_t* __restrict__ A, const bf16_t* __restrict__ Bt, int M, int N, int K, bf16_t* __restrict__ Out, int ldo,
;                     const float* __restrict__ rstd, const float* __restrict__ rope) {
;     ...
;           const int row = brow + ai * HALF + wr * 64 + m * 16 + fr;
;           float rs = 1.f; if constexpr (MODE == G_INPROJ) rs = rstd[row];
;     ...
; #pragma unroll
;     for (int a = 0; a < 2; ++a)
; #pragma unroll
;       for (int b = 0; b < 2; ++b)
; #pragma unroll
;         for (int m = 0; m < 4; ++m)
; #pragma unroll
;           for (int n = 0; n < 2; ++n) acc[a][b][m][n] = (f32x4){0.f, 0.f, 0.f, 0.f};
;     pm = npm; pn = npn; cA = nA; cB = nB; L += (int)gridDim.x;
.LBB0_127:
	s_ashr_i32 s19, s18, 31
	s_lshl_b64 s[22:23], s[18:19], 20
	s_add_u32 s19, s66, s22
	s_addc_u32 s42, s67, s23
	s_ashr_i32 s21, s20, 31
	s_lshl_b64 s[24:25], s[20:21], 20
	s_add_u32 s21, s58, s24
	s_addc_u32 s43, s59, s25
	s_add_u32 s44, s58, s26
	s_addc_u32 s45, s59, s27
	v_readlane_b32 s28, v254, 63
	s_add_u32 s46, s28, s8
	v_readlane_b32 s8, v255, 0
	v_mov_b32_e32 v0, 0
	s_addc_u32 s47, s8, s9
	s_mov_b32 s48, -2
	s_mov_b64 s[8:9], 0
	v_mov_b32_e32 v1, v0
	v_mov_b32_e32 v2, v0
	v_mov_b32_e32 v3, v0
	v_mov_b32_e32 v4, v0
	v_mov_b32_e32 v5, v0
	v_mov_b32_e32 v6, v0
	v_mov_b32_e32 v7, v0
	s_waitcnt vmcnt(0)
	v_mov_b32_e32 v16, v0
	v_mov_b32_e32 v17, v0
	v_mov_b32_e32 v18, v0
	v_mov_b32_e32 v19, v0
	v_mov_b32_e32 v20, v0
	v_mov_b32_e32 v21, v0
	v_mov_b32_e32 v22, v0
	v_mov_b32_e32 v23, v0
	v_mov_b32_e32 v32, v0
	s_waitcnt lgkmcnt(0)
	v_mov_b32_e32 v33, v0
	v_mov_b32_e32 v34, v0
	v_mov_b32_e32 v35, v0
	v_mov_b32_e32 v36, v0
	v_mov_b32_e32 v37, v0
	v_mov_b32_e32 v38, v0
	v_mov_b32_e32 v39, v0
	v_mov_b32_e32 v48, v0
	v_mov_b32_e32 v49, v0
	v_mov_b32_e32 v50, v0
	v_mov_b32_e32 v51, v0
	v_mov_b32_e32 v52, v0
	v_mov_b32_e32 v53, v0
	v_mov_b32_e32 v54, v0
	v_mov_b32_e32 v55, v0
	v_mov_b32_e32 v8, v0
	v_mov_b32_e32 v9, v0
	v_mov_b32_e32 v10, v0
	v_mov_b32_e32 v11, v0
	v_mov_b32_e32 v12, v0
	v_mov_b32_e32 v13, v0
	v_mov_b32_e32 v14, v0
	v_mov_b32_e32 v15, v0
	v_mov_b32_e32 v24, v0
	v_mov_b32_e32 v25, v0
	v_mov_b32_e32 v26, v0
	v_mov_b32_e32 v27, v0
	v_mov_b32_e32 v28, v0
	v_mov_b32_e32 v29, v0
	v_mov_b32_e32 v30, v0
	v_mov_b32_e32 v31, v0
	v_mov_b32_e32 v40, v0
	v_mov_b32_e32 v41, v0
	v_mov_b32_e32 v42, v0
	v_mov_b32_e32 v43, v0
	v_mov_b32_e32 v44, v0
	v_mov_b32_e32 v45, v0
	v_mov_b32_e32 v46, v0
	v_mov_b32_e32 v47, v0
	v_mov_b32_e32 v56, v0
	v_mov_b32_e32 v57, v0
	v_mov_b32_e32 v58, v0
	v_mov_b32_e32 v59, v0
	v_mov_b32_e32 v60, v0
	v_mov_b32_e32 v61, v0
	v_mov_b32_e32 v62, v0
	v_mov_b32_e32 v63, v0
	v_mov_b32_e32 v64, v0
	v_mov_b32_e32 v65, v0
	v_mov_b32_e32 v66, v0
	v_mov_b32_e32 v67, v0
	v_mov_b32_e32 v68, v0
	v_mov_b32_e32 v69, v0
	v_mov_b32_e32 v70, v0
	v_mov_b32_e32 v71, v0
	v_mov_b32_e32 v80, v0
	v_mov_b32_e32 v81, v0
	v_mov_b32_e32 v82, v0
	v_mov_b32_e32 v83, v0
	v_mov_b32_e32 v84, v0
	v_mov_b32_e32 v85, v0
	v_mov_b32_e32 v86, v0
	v_mov_b32_e32 v87, v0
	v_mov_b32_e32 v96, v0
	v_mov_b32_e32 v97, v0
	v_mov_b32_e32 v98, v0
	v_mov_b32_e32 v99, v0
	v_mov_b32_e32 v100, v0
	v_mov_b32_e32 v101, v0
	v_mov_b32_e32 v102, v0
	v_mov_b32_e32 v103, v0
	v_mov_b32_e32 v112, v0
	v_mov_b32_e32 v113, v0
	v_mov_b32_e32 v114, v0
	v_mov_b32_e32 v115, v0
	v_mov_b32_e32 v116, v0
	v_mov_b32_e32 v117, v0
	v_mov_b32_e32 v118, v0
	v_mov_b32_e32 v119, v0
	v_mov_b32_e32 v72, v0
	v_mov_b32_e32 v73, v0
	v_mov_b32_e32 v74, v0
	v_mov_b32_e32 v75, v0
	v_mov_b32_e32 v76, v0
	v_mov_b32_e32 v77, v0
	v_mov_b32_e32 v78, v0
	v_mov_b32_e32 v79, v0
	v_mov_b32_e32 v88, v0
	v_mov_b32_e32 v89, v0
	v_mov_b32_e32 v90, v0
	v_mov_b32_e32 v91, v0
	v_mov_b32_e32 v92, v0
	v_mov_b32_e32 v93, v0
	v_mov_b32_e32 v94, v0
	v_mov_b32_e32 v95, v0
	v_mov_b32_e32 v104, v0
	v_mov_b32_e32 v105, v0
	v_mov_b32_e32 v106, v0
	v_mov_b32_e32 v107, v0
	v_mov_b32_e32 v108, v0
	v_mov_b32_e32 v109, v0
	v_mov_b32_e32 v110, v0
	v_mov_b32_e32 v111, v0
	v_mov_b32_e32 v120, v0
	v_mov_b32_e32 v121, v0
	v_mov_b32_e32 v122, v0
	v_mov_b32_e32 v123, v0
	v_mov_b32_e32 v124, v0
	v_mov_b32_e32 v125, v0
	v_mov_b32_e32 v126, v0
	v_mov_b32_e32 v127, v0
	v_lshl_add_u64 v[128:129], v[160:161], 0, s[26:27]
	v_lshl_add_u64 v[130:131], v[162:163], 0, s[26:27]
	s_mov_b64 s[88:89], 0x80
	v_lshl_add_u32 v248, s41, 8, v170
	v_ashrrev_i32_e32 v249, 31, v248
	v_lshl_add_u64 v[248:249], v[248:249], 2, s[68:69]
	global_load_dword v232, v[248:249], off
	global_load_dword v234, v[248:249], off offset:64
	global_load_dword v236, v[248:249], off offset:128
	global_load_dword v238, v[248:249], off offset:192
	global_load_dword v240, v[248:249], off offset:512
	global_load_dword v242, v[248:249], off offset:576
	global_load_dword v244, v[248:249], off offset:640
	global_load_dword v246, v[248:249], off offset:704
	.p2align 6

; template <int MODE>
; DEV void gemm_phase(const bf16_t* __restrict__ A, const bf16_t* __restrict__ Bt, int M, int N, int K, bf16_t* __restrict__ Out, int ldo,
;                     const float* __restrict__ rstd, const float* __restrict__ rope) {
;     ...
;       const bool ropet = (MODE == G_INPROJ) && (pn >= 12 && pn < 20) && ((wc & 1) == 0);
; #pragma unroll
;       for (int ai = 0; ai < 2; ++ai)
; #pragma unroll
;         for (int m = 0; m < 4; ++m) {
;           const int row = brow + ai * HALF + wr * 64 + m * 16 + fr;
;           float rs = 1.f; if constexpr (MODE == G_INPROJ) rs = rstd[row];
; #pragma unroll
;           for (int bj = 0; bj < 2; ++bj) {
;             f32x4 v0 = acc[ai][bj][m][0], v1 = acc[ai][bj][m][1];
;             if constexpr (MODE == G_INPROJ) {
;               if (ropet) {
;                 const f32x4 c0 = *reinterpret_cast<const f32x4*>(rope + (size_t)row * 16), c1 = *reinterpret_cast<const f32x4*>(rope + (size_t)row * 16 + 4);
;                 const f32x4 s0 = *reinterpret_cast<const f32x4*>(rope + (size_t)row * 16 + 8), s1 = *reinterpret_cast<const f32x4*>(rope + (size_t)row * 16 + 12);
; #pragma unroll
;                 for (int j = 0; j < 4; ++j) { const float p0_ = __shfl_xor(v0[j], 16), p1_ = __shfl_xor(v1[j], 16);
;                   if (fq < 2) { v0[j] = (fq == 0) ? (v0[j] * c0[j] - p0_ * s0[j]) : (v0[j] * c0[j] + p0_ * s0[j]);
;                                 v1[j] = (fq == 0) ? (v1[j] * c1[j] - p1_ * s1[j]) : (v1[j] * c1[j] + p1_ * s1[j]); } }
.LBB0_131:
	v_lshl_add_u32 v164, s41, 8, v170
	v_ashrrev_i32_e32 v165, 31, v164
	v_lshl_add_u64 v[128:129], v[164:165], 2, s[68:69]
	v_mov_b32_e32 v194, v232
	v_mov_b32_e32 v196, v234
	v_mov_b32_e32 v198, v236
	v_mov_b32_e32 v200, v238
	v_mov_b32_e32 v202, v240
	v_mov_b32_e32 v204, v242
	v_mov_b32_e32 v206, v244
	v_mov_b32_e32 v208, v246
	s_add_i32 s8, s40, -12
	s_cmp_lt_u32 s8, 8
	s_cselect_b64 s[8:9], -1, 0
	s_and_b64 s[26:27], s[8:9], s[14:15]
	v_lshlrev_b64 v[128:129], 6, v[164:165]
	v_lshl_add_u64 v[168:169], s[72:73], 0, v[128:129]
	s_and_b64 vcc, exec, s[26:27]
	s_cbranch_vccz .LBB0_141
	global_load_dwordx4 v[132:135], v[168:169], off offset:48
	global_load_dwordx4 v[144:147], v[168:169], off offset:32
	global_load_dwordx4 v[128:131], v[168:169], off offset:16
	global_load_dwordx4 v[136:139], v[168:169], off
	v_and_b32_e32 v141, 64, v211
	v_xor_b32_e32 v140, 16, v211
	v_add_u32_e32 v141, 64, v141
	v_cmp_lt_i32_e32 vcc, v140, v141
	v_mov_b64_e32 v[150:151], v[122:123]
	v_mov_b64_e32 v[148:149], v[120:121]
	v_cndmask_b32_e32 v140, v211, v140, vcc
	v_lshlrev_b32_e32 v165, 2, v140
	ds_bpermute_b32 v173, v165, v124
	ds_bpermute_b32 v167, v165, v120
	v_mov_b64_e32 v[142:143], v[126:127]
	v_mov_b64_e32 v[140:141], v[124:125]
	s_and_saveexec_b64 s[8:9], s[4:5]
	s_cbranch_execz .LBB0_134
	s_waitcnt vmcnt(0) lgkmcnt(0)
	v_mul_f32_e32 v140, v144, v173
	v_cndmask_b32_e64 v144, v140, -v140, s[6:7]
	v_mov_b64_e32 v[142:143], v[126:127]
	v_fmac_f32_e32 v144, v124, v136
	v_mov_b64_e32 v[140:141], v[124:125]
	v_mul_f32_e32 v124, v132, v167
	v_cndmask_b32_e64 v124, v124, -v124, s[6:7]
	v_mov_b64_e32 v[150:151], v[122:123]
	v_fmac_f32_e32 v124, v120, v128
	v_mov_b64_e32 v[148:149], v[120:121]
	v_mov_b32_e32 v140, v144
	v_mov_b32_e32 v148, v124

; template <int MODE>
; DEV void gemm_phase(const bf16_t* __restrict__ A, const bf16_t* __restrict__ Bt, int M, int N, int K, bf16_t* __restrict__ Out, int ldo,
;                     const float* __restrict__ rstd, const float* __restrict__ rope) {
;     ...
;           const int row = brow + ai * HALF + wr * 64 + m * 16 + fr; const float rs = rstd[row];
;     ...
; #pragma unroll
;     for (int a = 0; a < 2; ++a)
; #pragma unroll
;       for (int b = 0; b < 2; ++b)
; #pragma unroll
;         for (int m = 0; m < 4; ++m)
; #pragma unroll
;           for (int n = 0; n < 2; ++n) acc[a][b][m][n] = (f32x4){0.f, 0.f, 0.f, 0.f};
;     pm = npm; pn = npn; cA = nA; cB = nB; L += (int)gridDim.x;
.LBB0_617:
	s_ashr_i32 s9, s8, 31
	s_lshl_b64 s[14:15], s[8:9], 20
	s_add_u32 s9, s66, s14
	s_addc_u32 s36, s67, s15
	s_ashr_i32 s11, s10, 31
	s_lshl_b64 s[16:17], s[10:11], 20
	s_add_u32 s11, s78, s16
	s_addc_u32 s37, s79, s17
	s_add_u32 s38, s58, s20
	s_addc_u32 s39, s59, s21
	v_lshl_add_u64 v[140:141], v[136:137], 0, s[20:21]
	v_lshl_add_u64 v[142:143], v[138:139], 0, s[20:21]
	v_readlane_b32 s20, v255, 3
	s_add_u32 s40, s20, s18
	v_readlane_b32 s18, v255, 4
	v_mov_b32_e32 v0, 0
	s_addc_u32 s41, s18, s19
	s_mov_b32 s42, -2
	s_mov_b64 s[18:19], 0
	v_mov_b32_e32 v1, v0
	v_mov_b32_e32 v2, v0
	v_mov_b32_e32 v3, v0
	v_mov_b32_e32 v8, v0
	v_mov_b32_e32 v9, v0
	v_mov_b32_e32 v10, v0
	v_mov_b32_e32 v11, v0
	v_mov_b32_e32 v16, v0
	v_mov_b32_e32 v17, v0
	v_mov_b32_e32 v18, v0
	v_mov_b32_e32 v19, v0
	v_mov_b32_e32 v20, v0
	v_mov_b32_e32 v21, v0
	v_mov_b32_e32 v22, v0
	v_mov_b32_e32 v23, v0
	v_mov_b32_e32 v32, v0
	v_mov_b32_e32 v33, v0
	v_mov_b32_e32 v34, v0
	v_mov_b32_e32 v35, v0
	v_mov_b32_e32 v36, v0
	v_mov_b32_e32 v37, v0
	v_mov_b32_e32 v38, v0
	v_mov_b32_e32 v39, v0
	v_mov_b32_e32 v48, v0
	v_mov_b32_e32 v49, v0
	v_mov_b32_e32 v50, v0
	v_mov_b32_e32 v51, v0
	v_mov_b32_e32 v52, v0
	v_mov_b32_e32 v53, v0
	v_mov_b32_e32 v54, v0
	v_mov_b32_e32 v55, v0
	v_mov_b32_e32 v4, v0
	v_mov_b32_e32 v5, v0
	v_mov_b32_e32 v6, v0
	v_mov_b32_e32 v7, v0
	v_mov_b32_e32 v12, v0
	v_mov_b32_e32 v13, v0
	v_mov_b32_e32 v14, v0
	v_mov_b32_e32 v15, v0
	v_mov_b32_e32 v24, v0
	v_mov_b32_e32 v25, v0
	v_mov_b32_e32 v26, v0
	v_mov_b32_e32 v27, v0
	v_mov_b32_e32 v28, v0
	v_mov_b32_e32 v29, v0
	v_mov_b32_e32 v30, v0
	v_mov_b32_e32 v31, v0
	v_mov_b32_e32 v40, v0
	v_mov_b32_e32 v41, v0
	v_mov_b32_e32 v42, v0
	v_mov_b32_e32 v43, v0
	v_mov_b32_e32 v44, v0
	v_mov_b32_e32 v45, v0
	v_mov_b32_e32 v46, v0
	v_mov_b32_e32 v47, v0
	v_mov_b32_e32 v56, v0
	v_mov_b32_e32 v57, v0
	v_mov_b32_e32 v58, v0
	v_mov_b32_e32 v59, v0
	v_mov_b32_e32 v60, v0
	v_mov_b32_e32 v61, v0
	v_mov_b32_e32 v62, v0
	v_mov_b32_e32 v63, v0
	v_mov_b32_e32 v64, v0
	v_mov_b32_e32 v65, v0
	v_mov_b32_e32 v66, v0
	v_mov_b32_e32 v67, v0
	v_mov_b32_e32 v68, v0
	v_mov_b32_e32 v69, v0
	v_mov_b32_e32 v70, v0
	v_mov_b32_e32 v71, v0
	v_mov_b32_e32 v80, v0
	v_mov_b32_e32 v81, v0
	v_mov_b32_e32 v82, v0
	v_mov_b32_e32 v83, v0
	v_mov_b32_e32 v84, v0
	v_mov_b32_e32 v85, v0
	v_mov_b32_e32 v86, v0
	v_mov_b32_e32 v87, v0
	v_mov_b32_e32 v96, v0
	v_mov_b32_e32 v97, v0
	v_mov_b32_e32 v98, v0
	v_mov_b32_e32 v99, v0
	v_mov_b32_e32 v100, v0
	v_mov_b32_e32 v101, v0
	v_mov_b32_e32 v102, v0
	v_mov_b32_e32 v103, v0
	v_mov_b32_e32 v112, v0
	v_mov_b32_e32 v113, v0
	v_mov_b32_e32 v114, v0
	v_mov_b32_e32 v115, v0
	v_mov_b32_e32 v116, v0
	v_mov_b32_e32 v117, v0
	v_mov_b32_e32 v118, v0
	v_mov_b32_e32 v119, v0
	v_mov_b32_e32 v72, v0
	v_mov_b32_e32 v73, v0
	v_mov_b32_e32 v74, v0
	v_mov_b32_e32 v75, v0
	v_mov_b32_e32 v76, v0
	v_mov_b32_e32 v77, v0
	v_mov_b32_e32 v78, v0
	v_mov_b32_e32 v79, v0
	v_mov_b32_e32 v88, v0
	v_mov_b32_e32 v89, v0
	v_mov_b32_e32 v90, v0
	v_mov_b32_e32 v91, v0
	v_mov_b32_e32 v92, v0
	v_mov_b32_e32 v93, v0
	v_mov_b32_e32 v94, v0
	v_mov_b32_e32 v95, v0
	v_mov_b32_e32 v104, v0
	v_mov_b32_e32 v105, v0
	v_mov_b32_e32 v106, v0
	v_mov_b32_e32 v107, v0
	v_mov_b32_e32 v108, v0
	v_mov_b32_e32 v109, v0
	v_mov_b32_e32 v110, v0
	v_mov_b32_e32 v111, v0
	v_mov_b32_e32 v120, v0
	v_mov_b32_e32 v121, v0
	v_mov_b32_e32 v122, v0
	v_mov_b32_e32 v123, v0
	v_mov_b32_e32 v124, v0
	v_mov_b32_e32 v125, v0
	v_mov_b32_e32 v126, v0
	v_mov_b32_e32 v127, v0
	s_mov_b64 s[46:47], 0x80
	v_lshl_add_u32 v248, s35, 8, v144
	v_ashrrev_i32_e32 v249, 31, v248
	v_lshl_add_u64 v[248:249], v[248:249], 2, s[68:69]
	global_load_dword v232, v[248:249], off
	global_load_dword v234, v[248:249], off offset:64
	global_load_dword v236, v[248:249], off offset:128
	global_load_dword v238, v[248:249], off offset:192
	global_load_dword v240, v[248:249], off offset:512
	global_load_dword v242, v[248:249], off offset:576
	global_load_dword v244, v[248:249], off offset:640
	global_load_dword v246, v[248:249], off offset:704
	.p2align 6

; DEV unsigned cvtpk(float lo, float hi) { f32x2_t v = {lo, hi}; bf16x2_t b = __builtin_convertvector(v, bf16x2_t); return __builtin_bit_cast(unsigned, b); }
; template <int MODE>
; DEV void gemm_phase(const bf16_t* __restrict__ A, const bf16_t* __restrict__ Bt, int M, int N, int K, bf16_t* __restrict__ Out, int ldo,
;                     const float* __restrict__ rstd, const float* __restrict__ rope) {
;     ...
;     if constexpr (MODE == G_GATEUP) {
; #pragma unroll
;       for (int ai = 0; ai < 2; ++ai)
; #pragma unroll
;         for (int m = 0; m < 4; ++m) {
;           const int row = brow + ai * HALF + wr * 64 + m * 16 + fr; const float rs = rstd[row];
;           float a8[8];
; #pragma unroll
;           for (int n = 0; n < 2; ++n)
; #pragma unroll
;             for (int j = 0; j < 4; ++j) { const float gv = acc[ai][0][m][n][j] * rs, uv = acc[ai][1][m][n][j] * rs;
;               a8[n * 4 + j] = gv * __builtin_amdgcn_rcpf(1.f + __builtin_amdgcn_exp2f(-gv * LOG2E)) * uv; }
;           u32x4 w = {cvtpk(a8[0], a8[1]), cvtpk(a8[2], a8[3]), cvtpk(a8[4], a8[5]), cvtpk(a8[6], a8[7])};
;           *reinterpret_cast<u32x4*>(Out + (size_t)row * ldo + pn * 128 + wc * 32 + fq * 8) = w; }
.LBB0_621:
	v_lshl_add_u32 v142, s35, 8, v144
	v_ashrrev_i32_e32 v143, 31, v142
	v_lshl_add_u64 v[148:149], v[142:143], 2, s[68:69]
	v_mov_b32_e32 v152, v232
	v_mov_b32_e32 v154, v234
	v_mov_b32_e32 v156, v236
	v_mov_b32_e32 v158, v238
	v_mov_b32_e32 v160, v240
	v_mov_b32_e32 v162, v242
	v_mov_b32_e32 v164, v244
	v_mov_b32_e32 v166, v246
	s_lshl_b32 s18, s34, 7
	s_ashr_i32 s19, s18, 31
	v_lshl_add_u64 v[140:141], s[18:19], 1, v[134:135]
	s_movk_i32 s9, 0x2c00
	s_andn2_b64 vcc, exec, s[12:13]
	s_waitcnt vmcnt(0)
	v_pk_mul_f32 v[124:125], v[124:125], v[152:153] op_sel_hi:[1,0]
	s_nop 0
	v_mul_f32_e32 v143, 0xbfb8aa3b, v124
	v_exp_f32_e32 v143, v143
	v_pk_mul_f32 v[116:117], v[116:117], v[152:153] op_sel_hi:[1,0]
	v_pk_mul_f32 v[118:119], v[118:119], v[152:153] op_sel_hi:[1,0]
	v_pk_mul_f32 v[120:121], v[120:121], v[152:153] op_sel_hi:[1,0]
	v_add_f32_e32 v143, 1.0, v143
	v_rcp_f32_e32 v150, v143
	v_mul_f32_e32 v143, 0xbfb8aa3b, v125
	v_exp_f32_e32 v143, v143
	v_pk_mul_f32 v[112:113], v[112:113], v[152:153] op_sel_hi:[1,0]
	v_pk_mul_f32 v[114:115], v[114:115], v[152:153] op_sel_hi:[1,0]
	v_add_f32_e32 v143, 1.0, v143
	v_rcp_f32_e32 v151, v143
	s_nop 0
	v_pk_mul_f32 v[124:125], v[124:125], v[150:151]
	s_nop 0
	v_pk_mul_f32 v[116:117], v[116:117], v[124:125]
	v_pk_mul_f32 v[124:125], v[126:127], v[152:153] op_sel_hi:[1,0]
	s_nop 0
	v_mul_f32_e32 v126, 0xbfb8aa3b, v124
	v_mul_f32_e32 v127, 0xbfb8aa3b, v125
	v_exp_f32_e32 v126, v126
	v_exp_f32_e32 v127, v127
	v_add_f32_e32 v126, 1.0, v126
	v_add_f32_e32 v127, 1.0, v127
	v_rcp_f32_e32 v126, v126
	v_rcp_f32_e32 v127, v127
	s_nop 0
	v_pk_mul_f32 v[124:125], v[124:125], v[126:127]
	s_nop 0
	v_pk_mul_f32 v[118:119], v[118:119], v[124:125]
	v_mul_f32_e32 v124, 0xbfb8aa3b, v120
	v_mul_f32_e32 v125, 0xbfb8aa3b, v121
	v_exp_f32_e32 v124, v124
	v_exp_f32_e32 v125, v125
	v_add_f32_e32 v124, 1.0, v124
	v_add_f32_e32 v125, 1.0, v125
	v_rcp_f32_e32 v124, v124
	v_rcp_f32_e32 v125, v125
	s_nop 0
	v_pk_mul_f32 v[120:121], v[120:121], v[124:125]
	s_nop 0
	v_pk_mul_f32 v[120:121], v[112:113], v[120:121]
	v_pk_mul_f32 v[112:113], v[122:123], v[152:153] op_sel_hi:[1,0]
	s_nop 0
	v_mul_f32_e32 v122, 0xbfb8aa3b, v112
	v_mul_f32_e32 v123, 0xbfb8aa3b, v113
	v_exp_f32_e32 v122, v122
	v_exp_f32_e32 v123, v123
	v_add_f32_e32 v122, 1.0, v122
	v_add_f32_e32 v123, 1.0, v123
	v_rcp_f32_e32 v122, v122
	v_rcp_f32_e32 v123, v123
	s_nop 0
	v_pk_mul_f32 v[112:113], v[112:113], v[122:123]
	s_nop 0
	v_pk_mul_f32 v[122:123], v[114:115], v[112:113]
	v_cvt_pk_bf16_f32 v112, v116, v117
	v_cvt_pk_bf16_f32 v113, v118, v119
	v_cvt_pk_bf16_f32 v114, v120, v121
	v_cvt_pk_bf16_f32 v115, v122, v123
	v_mad_i64_i32 v[116:117], s[18:19], v142, s9, v[140:141]
	global_store_dwordx4 v[116:117], v[112:115], off
	s_nop 1
	v_or_b32_e32 v112, 16, v142
	v_pk_mul_f32 v[108:109], v[108:109], v[154:155] op_sel_hi:[1,0]
	s_nop 0
	v_mul_f32_e32 v113, 0xbfb8aa3b, v108
	v_exp_f32_e32 v113, v113
	v_pk_mul_f32 v[100:101], v[100:101], v[154:155] op_sel_hi:[1,0]
	v_pk_mul_f32 v[102:103], v[102:103], v[154:155] op_sel_hi:[1,0]
	v_pk_mul_f32 v[104:105], v[104:105], v[154:155] op_sel_hi:[1,0]
	v_add_f32_e32 v113, 1.0, v113
	v_rcp_f32_e32 v116, v113
	v_mul_f32_e32 v113, 0xbfb8aa3b, v109
	v_exp_f32_e32 v113, v113
	v_pk_mul_f32 v[96:97], v[96:97], v[154:155] op_sel_hi:[1,0]
	v_pk_mul_f32 v[98:99], v[98:99], v[154:155] op_sel_hi:[1,0]
	v_add_f32_e32 v113, 1.0, v113
	v_rcp_f32_e32 v117, v113
	s_nop 0
	v_pk_mul_f32 v[108:109], v[108:109], v[116:117]
	s_nop 0
	v_pk_mul_f32 v[100:101], v[100:101], v[108:109]
	v_pk_mul_f32 v[108:109], v[110:111], v[154:155] op_sel_hi:[1,0]
	s_nop 0
	v_mul_f32_e32 v110, 0xbfb8aa3b, v108
	v_mul_f32_e32 v111, 0xbfb8aa3b, v109
	v_exp_f32_e32 v110, v110
	v_exp_f32_e32 v111, v111
	v_add_f32_e32 v110, 1.0, v110
	v_add_f32_e32 v111, 1.0, v111
	v_rcp_f32_e32 v110, v110
	v_rcp_f32_e32 v111, v111
	s_nop 0
	v_pk_mul_f32 v[108:109], v[108:109], v[110:111]
	s_nop 0
	v_pk_mul_f32 v[102:103], v[102:103], v[108:109]
	v_mul_f32_e32 v108, 0xbfb8aa3b, v104
	v_mul_f32_e32 v109, 0xbfb8aa3b, v105
	v_exp_f32_e32 v108, v108
	v_exp_f32_e32 v109, v109
	v_add_f32_e32 v108, 1.0, v108
	v_add_f32_e32 v109, 1.0, v109
	v_rcp_f32_e32 v108, v108
	v_rcp_f32_e32 v109, v109
	s_nop 0
	v_pk_mul_f32 v[104:105], v[104:105], v[108:109]
	s_nop 0
	v_pk_mul_f32 v[104:105], v[96:97], v[104:105]
	v_pk_mul_f32 v[96:97], v[106:107], v[154:155] op_sel_hi:[1,0]
	s_nop 0
	v_mul_f32_e32 v106, 0xbfb8aa3b, v96
	v_mul_f32_e32 v107, 0xbfb8aa3b, v97
	v_exp_f32_e32 v106, v106
	v_exp_f32_e32 v107, v107
	v_add_f32_e32 v106, 1.0, v106
	v_add_f32_e32 v107, 1.0, v107
	v_rcp_f32_e32 v106, v106
	v_rcp_f32_e32 v107, v107
	s_nop 0
	v_pk_mul_f32 v[96:97], v[96:97], v[106:107]
	s_nop 0
	v_pk_mul_f32 v[106:107], v[98:99], v[96:97]
	v_cvt_pk_bf16_f32 v96, v100, v101
	v_cvt_pk_bf16_f32 v97, v102, v103
	v_cvt_pk_bf16_f32 v98, v104, v105
	v_cvt_pk_bf16_f32 v99, v106, v107
	v_mad_i64_i32 v[100:101], s[18:19], v112, s9, v[140:141]
	global_store_dwordx4 v[100:101], v[96:99], off
	s_nop 1
	v_or_b32_e32 v96, 32, v142
	v_pk_mul_f32 v[92:93], v[92:93], v[156:157] op_sel_hi:[1,0]
	s_nop 0
	v_mul_f32_e32 v97, 0xbfb8aa3b, v92
	v_exp_f32_e32 v97, v97
	v_pk_mul_f32 v[84:85], v[84:85], v[156:157] op_sel_hi:[1,0]
	v_pk_mul_f32 v[86:87], v[86:87], v[156:157] op_sel_hi:[1,0]
	v_pk_mul_f32 v[88:89], v[88:89], v[156:157] op_sel_hi:[1,0]
	v_add_f32_e32 v97, 1.0, v97
	v_rcp_f32_e32 v100, v97
	v_mul_f32_e32 v97, 0xbfb8aa3b, v93
	v_exp_f32_e32 v97, v97
	v_pk_mul_f32 v[80:81], v[80:81], v[156:157] op_sel_hi:[1,0]
	v_pk_mul_f32 v[82:83], v[82:83], v[156:157] op_sel_hi:[1,0]
	v_add_f32_e32 v97, 1.0, v97
	v_rcp_f32_e32 v101, v97
	s_nop 0
; DEV unsigned cvtpk(float lo, float hi) { f32x2_t v = {lo, hi}; bf16x2_t b = __builtin_convertvector(v, bf16x2_t); return __builtin_bit_cast(unsigned, b); }
; template <int MODE>
; DEV void gemm_phase(const bf16_t* __restrict__ A, const bf16_t* __restrict__ Bt, int M, int N, int K, bf16_t* __restrict__ Out, int ldo,
;                     const float* __restrict__ rstd, const float* __restrict__ rope) {
;     ...
;     if constexpr (MODE == G_GATEUP) {
; #pragma unroll
;       for (int ai = 0; ai < 2; ++ai)
; #pragma unroll
;         for (int m = 0; m < 4; ++m) {
;           const int row = brow + ai * HALF + wr * 64 + m * 16 + fr; const float rs = rstd[row];
;           float a8[8];
; #pragma unroll
;           for (int n = 0; n < 2; ++n)
; #pragma unroll
;             for (int j = 0; j < 4; ++j) { const float gv = acc[ai][0][m][n][j] * rs, uv = acc[ai][1][m][n][j] * rs;
;               a8[n * 4 + j] = gv * __builtin_amdgcn_rcpf(1.f + __builtin_amdgcn_exp2f(-gv * LOG2E)) * uv; }
;           u32x4 w = {cvtpk(a8[0], a8[1]), cvtpk(a8[2], a8[3]), cvtpk(a8[4], a8[5]), cvtpk(a8[6], a8[7])};
;           *reinterpret_cast<u32x4*>(Out + (size_t)row * ldo + pn * 128 + wc * 32 + fq * 8) = w; }
	v_pk_mul_f32 v[92:93], v[92:93], v[100:101]
	s_nop 0
	v_pk_mul_f32 v[84:85], v[84:85], v[92:93]
	v_pk_mul_f32 v[92:93], v[94:95], v[156:157] op_sel_hi:[1,0]
	s_nop 0
	v_mul_f32_e32 v94, 0xbfb8aa3b, v92
	v_mul_f32_e32 v95, 0xbfb8aa3b, v93
	v_exp_f32_e32 v94, v94
	v_exp_f32_e32 v95, v95
	v_add_f32_e32 v94, 1.0, v94
	v_add_f32_e32 v95, 1.0, v95
	v_rcp_f32_e32 v94, v94
	v_rcp_f32_e32 v95, v95
	s_nop 0
	v_pk_mul_f32 v[92:93], v[92:93], v[94:95]
	s_nop 0
	v_pk_mul_f32 v[86:87], v[86:87], v[92:93]
	v_mul_f32_e32 v92, 0xbfb8aa3b, v88
	v_mul_f32_e32 v93, 0xbfb8aa3b, v89
	v_exp_f32_e32 v92, v92
	v_exp_f32_e32 v93, v93
	v_add_f32_e32 v92, 1.0, v92
	v_add_f32_e32 v93, 1.0, v93
	v_rcp_f32_e32 v92, v92
	v_rcp_f32_e32 v93, v93
	s_nop 0
	v_pk_mul_f32 v[88:89], v[88:89], v[92:93]
	s_nop 0
	v_pk_mul_f32 v[88:89], v[80:81], v[88:89]
	v_pk_mul_f32 v[80:81], v[90:91], v[156:157] op_sel_hi:[1,0]
	s_nop 0
	v_mul_f32_e32 v90, 0xbfb8aa3b, v80
	v_mul_f32_e32 v91, 0xbfb8aa3b, v81
	v_exp_f32_e32 v90, v90
	v_exp_f32_e32 v91, v91
	v_add_f32_e32 v90, 1.0, v90
	v_add_f32_e32 v91, 1.0, v91
	v_rcp_f32_e32 v90, v90
	v_rcp_f32_e32 v91, v91
	s_nop 0
	v_pk_mul_f32 v[80:81], v[80:81], v[90:91]
	s_nop 0
	v_pk_mul_f32 v[90:91], v[82:83], v[80:81]
	v_cvt_pk_bf16_f32 v80, v84, v85
	v_cvt_pk_bf16_f32 v81, v86, v87
	v_cvt_pk_bf16_f32 v82, v88, v89
	v_cvt_pk_bf16_f32 v83, v90, v91
	v_mad_i64_i32 v[84:85], s[18:19], v96, s9, v[140:141]
	global_store_dwordx4 v[84:85], v[80:83], off
	s_nop 1
	v_or_b32_e32 v80, 48, v142
	v_pk_mul_f32 v[76:77], v[76:77], v[158:159] op_sel_hi:[1,0]
	s_nop 0
	v_mul_f32_e32 v81, 0xbfb8aa3b, v76
	v_exp_f32_e32 v81, v81
	v_pk_mul_f32 v[68:69], v[68:69], v[158:159] op_sel_hi:[1,0]
	v_pk_mul_f32 v[70:71], v[70:71], v[158:159] op_sel_hi:[1,0]
	v_pk_mul_f32 v[72:73], v[72:73], v[158:159] op_sel_hi:[1,0]
	v_add_f32_e32 v81, 1.0, v81
	v_rcp_f32_e32 v84, v81
	v_mul_f32_e32 v81, 0xbfb8aa3b, v77
	v_exp_f32_e32 v81, v81
	v_pk_mul_f32 v[64:65], v[64:65], v[158:159] op_sel_hi:[1,0]
	v_pk_mul_f32 v[66:67], v[66:67], v[158:159] op_sel_hi:[1,0]
	v_add_f32_e32 v81, 1.0, v81
	v_rcp_f32_e32 v85, v81
	s_nop 0
	v_pk_mul_f32 v[76:77], v[76:77], v[84:85]
	s_nop 0
	v_pk_mul_f32 v[68:69], v[68:69], v[76:77]
	v_pk_mul_f32 v[76:77], v[78:79], v[158:159] op_sel_hi:[1,0]
	s_nop 0
	v_mul_f32_e32 v78, 0xbfb8aa3b, v76
	v_mul_f32_e32 v79, 0xbfb8aa3b, v77
	v_exp_f32_e32 v78, v78
	v_exp_f32_e32 v79, v79
	v_add_f32_e32 v78, 1.0, v78
	v_add_f32_e32 v79, 1.0, v79
	v_rcp_f32_e32 v78, v78
	v_rcp_f32_e32 v79, v79
	s_nop 0
	v_pk_mul_f32 v[76:77], v[76:77], v[78:79]
	s_nop 0
	v_pk_mul_f32 v[70:71], v[70:71], v[76:77]
	v_mul_f32_e32 v76, 0xbfb8aa3b, v72
	v_mul_f32_e32 v77, 0xbfb8aa3b, v73
	v_exp_f32_e32 v76, v76
	v_exp_f32_e32 v77, v77
	v_add_f32_e32 v76, 1.0, v76
	v_add_f32_e32 v77, 1.0, v77
	v_rcp_f32_e32 v76, v76
	v_rcp_f32_e32 v77, v77
	s_nop 0
	v_pk_mul_f32 v[72:73], v[72:73], v[76:77]
	s_nop 0
	v_pk_mul_f32 v[72:73], v[64:65], v[72:73]
	v_pk_mul_f32 v[64:65], v[74:75], v[158:159] op_sel_hi:[1,0]
	s_nop 0
	v_mul_f32_e32 v74, 0xbfb8aa3b, v64
	v_mul_f32_e32 v75, 0xbfb8aa3b, v65
	v_exp_f32_e32 v74, v74
	v_exp_f32_e32 v75, v75
	v_add_f32_e32 v74, 1.0, v74
	v_add_f32_e32 v75, 1.0, v75
	v_rcp_f32_e32 v74, v74
	v_rcp_f32_e32 v75, v75
	s_nop 0
	v_pk_mul_f32 v[64:65], v[64:65], v[74:75]
	s_nop 0
	v_pk_mul_f32 v[74:75], v[66:67], v[64:65]
	v_cvt_pk_bf16_f32 v64, v68, v69
	v_cvt_pk_bf16_f32 v65, v70, v71
	v_cvt_pk_bf16_f32 v66, v72, v73
	v_cvt_pk_bf16_f32 v67, v74, v75
	v_mad_i64_i32 v[68:69], s[18:19], v80, s9, v[140:141]
	global_store_dwordx4 v[68:69], v[64:67], off
	s_nop 1
	v_add_u32_e32 v64, 0x80, v142
	v_pk_mul_f32 v[60:61], v[60:61], v[160:161] op_sel_hi:[1,0]
	s_nop 0
	v_mul_f32_e32 v65, 0xbfb8aa3b, v60
	v_exp_f32_e32 v65, v65
	v_pk_mul_f32 v[52:53], v[52:53], v[160:161] op_sel_hi:[1,0]
	v_pk_mul_f32 v[54:55], v[54:55], v[160:161] op_sel_hi:[1,0]
	v_pk_mul_f32 v[56:57], v[56:57], v[160:161] op_sel_hi:[1,0]
	v_add_f32_e32 v65, 1.0, v65
	v_rcp_f32_e32 v68, v65
	v_mul_f32_e32 v65, 0xbfb8aa3b, v61
	v_exp_f32_e32 v65, v65
	v_pk_mul_f32 v[48:49], v[48:49], v[160:161] op_sel_hi:[1,0]
	v_pk_mul_f32 v[50:51], v[50:51], v[160:161] op_sel_hi:[1,0]
	v_add_f32_e32 v65, 1.0, v65
	v_rcp_f32_e32 v69, v65
	s_nop 0
	v_pk_mul_f32 v[60:61], v[60:61], v[68:69]
	s_nop 0
	v_pk_mul_f32 v[52:53], v[52:53], v[60:61]
	v_pk_mul_f32 v[60:61], v[62:63], v[160:161] op_sel_hi:[1,0]
	s_nop 0
	v_mul_f32_e32 v62, 0xbfb8aa3b, v60
	v_mul_f32_e32 v63, 0xbfb8aa3b, v61
	v_exp_f32_e32 v62, v62
	v_exp_f32_e32 v63, v63
	v_add_f32_e32 v62, 1.0, v62
	v_add_f32_e32 v63, 1.0, v63
	v_rcp_f32_e32 v62, v62
	v_rcp_f32_e32 v63, v63
	s_nop 0
	v_pk_mul_f32 v[60:61], v[60:61], v[62:63]
	s_nop 0
	v_pk_mul_f32 v[54:55], v[54:55], v[60:61]
	v_mul_f32_e32 v60, 0xbfb8aa3b, v56
	v_mul_f32_e32 v61, 0xbfb8aa3b, v57
	v_exp_f32_e32 v60, v60
	v_exp_f32_e32 v61, v61
	v_add_f32_e32 v60, 1.0, v60
	v_add_f32_e32 v61, 1.0, v61
	v_rcp_f32_e32 v60, v60
	v_rcp_f32_e32 v61, v61
	s_nop 0
	v_pk_mul_f32 v[56:57], v[56:57], v[60:61]
	s_nop 0
	v_pk_mul_f32 v[56:57], v[48:49], v[56:57]
	v_pk_mul_f32 v[48:49], v[58:59], v[160:161] op_sel_hi:[1,0]
	s_nop 0
	v_mul_f32_e32 v58, 0xbfb8aa3b, v48
	v_mul_f32_e32 v59, 0xbfb8aa3b, v49
	v_exp_f32_e32 v58, v58
	v_exp_f32_e32 v59, v59
	v_add_f32_e32 v58, 1.0, v58
	v_add_f32_e32 v59, 1.0, v59
	v_rcp_f32_e32 v58, v58
	v_rcp_f32_e32 v59, v59
	s_nop 0
	v_pk_mul_f32 v[48:49], v[48:49], v[58:59]
	s_nop 0
	v_pk_mul_f32 v[58:59], v[50:51], v[48:49]
	v_cvt_pk_bf16_f32 v48, v52, v53
	v_cvt_pk_bf16_f32 v49, v54, v55
	v_cvt_pk_bf16_f32 v50, v56, v57
	v_cvt_pk_bf16_f32 v51, v58, v59
	v_mad_i64_i32 v[52:53], s[18:19], v64, s9, v[140:141]
; DEV unsigned cvtpk(float lo, float hi) { f32x2_t v = {lo, hi}; bf16x2_t b = __builtin_convertvector(v, bf16x2_t); return __builtin_bit_cast(unsigned, b); }
; template <int MODE>
; DEV void gemm_phase(const bf16_t* __restrict__ A, const bf16_t* __restrict__ Bt, int M, int N, int K, bf16_t* __restrict__ Out, int ldo,
;                     const float* __restrict__ rstd, const float* __restrict__ rope) {
;     ...
;     if constexpr (MODE == G_GATEUP) {
; #pragma unroll
;       for (int ai = 0; ai < 2; ++ai)
; #pragma unroll
;         for (int m = 0; m < 4; ++m) {
;           const int row = brow + ai * HALF + wr * 64 + m * 16 + fr; const float rs = rstd[row];
;           float a8[8];
; #pragma unroll
;           for (int n = 0; n < 2; ++n)
; #pragma unroll
;             for (int j = 0; j < 4; ++j) { const float gv = acc[ai][0][m][n][j] * rs, uv = acc[ai][1][m][n][j] * rs;
;               a8[n * 4 + j] = gv * __builtin_amdgcn_rcpf(1.f + __builtin_amdgcn_exp2f(-gv * LOG2E)) * uv; }
;           u32x4 w = {cvtpk(a8[0], a8[1]), cvtpk(a8[2], a8[3]), cvtpk(a8[4], a8[5]), cvtpk(a8[6], a8[7])};
;           *reinterpret_cast<u32x4*>(Out + (size_t)row * ldo + pn * 128 + wc * 32 + fq * 8) = w; }
	global_store_dwordx4 v[52:53], v[48:51], off
	s_nop 1
	v_add_u32_e32 v48, 0x90, v142
	v_pk_mul_f32 v[44:45], v[44:45], v[162:163] op_sel_hi:[1,0]
	s_nop 0
	v_mul_f32_e32 v49, 0xbfb8aa3b, v44
	v_exp_f32_e32 v49, v49
	v_pk_mul_f32 v[36:37], v[36:37], v[162:163] op_sel_hi:[1,0]
	v_pk_mul_f32 v[38:39], v[38:39], v[162:163] op_sel_hi:[1,0]
	v_pk_mul_f32 v[40:41], v[40:41], v[162:163] op_sel_hi:[1,0]
	v_add_f32_e32 v49, 1.0, v49
	v_rcp_f32_e32 v52, v49
	v_mul_f32_e32 v49, 0xbfb8aa3b, v45
	v_exp_f32_e32 v49, v49
	v_pk_mul_f32 v[32:33], v[32:33], v[162:163] op_sel_hi:[1,0]
	v_pk_mul_f32 v[34:35], v[34:35], v[162:163] op_sel_hi:[1,0]
	v_add_f32_e32 v49, 1.0, v49
	v_rcp_f32_e32 v53, v49
	s_nop 0
	v_pk_mul_f32 v[44:45], v[44:45], v[52:53]
	s_nop 0
	v_pk_mul_f32 v[36:37], v[36:37], v[44:45]
	v_pk_mul_f32 v[44:45], v[46:47], v[162:163] op_sel_hi:[1,0]
	s_nop 0
	v_mul_f32_e32 v46, 0xbfb8aa3b, v44
	v_mul_f32_e32 v47, 0xbfb8aa3b, v45
	v_exp_f32_e32 v46, v46
	v_exp_f32_e32 v47, v47
	v_add_f32_e32 v46, 1.0, v46
	v_add_f32_e32 v47, 1.0, v47
	v_rcp_f32_e32 v46, v46
	v_rcp_f32_e32 v47, v47
	s_nop 0
	v_pk_mul_f32 v[44:45], v[44:45], v[46:47]
	s_nop 0
	v_pk_mul_f32 v[38:39], v[38:39], v[44:45]
	v_mul_f32_e32 v44, 0xbfb8aa3b, v40
	v_mul_f32_e32 v45, 0xbfb8aa3b, v41
	v_exp_f32_e32 v44, v44
	v_exp_f32_e32 v45, v45
	v_add_f32_e32 v44, 1.0, v44
	v_add_f32_e32 v45, 1.0, v45
	v_rcp_f32_e32 v44, v44
	v_rcp_f32_e32 v45, v45
	s_nop 0
	v_pk_mul_f32 v[40:41], v[40:41], v[44:45]
	s_nop 0
	v_pk_mul_f32 v[40:41], v[32:33], v[40:41]
	v_pk_mul_f32 v[32:33], v[42:43], v[162:163] op_sel_hi:[1,0]
	s_nop 0
	v_mul_f32_e32 v42, 0xbfb8aa3b, v32
	v_mul_f32_e32 v43, 0xbfb8aa3b, v33
	v_exp_f32_e32 v42, v42
	v_exp_f32_e32 v43, v43
	v_add_f32_e32 v42, 1.0, v42
	v_add_f32_e32 v43, 1.0, v43
	v_rcp_f32_e32 v42, v42
	v_rcp_f32_e32 v43, v43
	s_nop 0
	v_pk_mul_f32 v[32:33], v[32:33], v[42:43]
	s_nop 0
	v_pk_mul_f32 v[42:43], v[34:35], v[32:33]
	v_cvt_pk_bf16_f32 v32, v36, v37
	v_cvt_pk_bf16_f32 v33, v38, v39
	v_cvt_pk_bf16_f32 v34, v40, v41
	v_cvt_pk_bf16_f32 v35, v42, v43
	v_mad_i64_i32 v[36:37], s[18:19], v48, s9, v[140:141]
	global_store_dwordx4 v[36:37], v[32:35], off
	s_nop 1
	v_add_u32_e32 v32, 0xa0, v142
	v_pk_mul_f32 v[28:29], v[28:29], v[164:165] op_sel_hi:[1,0]
	s_nop 0
	v_mul_f32_e32 v33, 0xbfb8aa3b, v28
	v_exp_f32_e32 v33, v33
	v_pk_mul_f32 v[20:21], v[20:21], v[164:165] op_sel_hi:[1,0]
	v_pk_mul_f32 v[22:23], v[22:23], v[164:165] op_sel_hi:[1,0]
	v_pk_mul_f32 v[24:25], v[24:25], v[164:165] op_sel_hi:[1,0]
	v_add_f32_e32 v33, 1.0, v33
	v_rcp_f32_e32 v36, v33
	v_mul_f32_e32 v33, 0xbfb8aa3b, v29
	v_exp_f32_e32 v33, v33
	v_pk_mul_f32 v[16:17], v[16:17], v[164:165] op_sel_hi:[1,0]
	v_pk_mul_f32 v[18:19], v[18:19], v[164:165] op_sel_hi:[1,0]
	v_add_f32_e32 v33, 1.0, v33
	v_rcp_f32_e32 v37, v33
	s_nop 0
	v_pk_mul_f32 v[28:29], v[28:29], v[36:37]
	s_nop 0
	v_pk_mul_f32 v[20:21], v[20:21], v[28:29]
	v_pk_mul_f32 v[28:29], v[30:31], v[164:165] op_sel_hi:[1,0]
	s_nop 0
	v_mul_f32_e32 v30, 0xbfb8aa3b, v28
	v_mul_f32_e32 v31, 0xbfb8aa3b, v29
	v_exp_f32_e32 v30, v30
	v_exp_f32_e32 v31, v31
	v_add_f32_e32 v30, 1.0, v30
	v_add_f32_e32 v31, 1.0, v31
	v_rcp_f32_e32 v30, v30
	v_rcp_f32_e32 v31, v31
	s_nop 0
	v_pk_mul_f32 v[28:29], v[28:29], v[30:31]
	s_nop 0
	v_pk_mul_f32 v[22:23], v[22:23], v[28:29]
	v_mul_f32_e32 v28, 0xbfb8aa3b, v24
	v_mul_f32_e32 v29, 0xbfb8aa3b, v25
	v_exp_f32_e32 v28, v28
	v_exp_f32_e32 v29, v29
	v_add_f32_e32 v28, 1.0, v28
	v_add_f32_e32 v29, 1.0, v29
	v_rcp_f32_e32 v28, v28
	v_rcp_f32_e32 v29, v29
	s_nop 0
	v_pk_mul_f32 v[24:25], v[24:25], v[28:29]
	s_nop 0
	v_pk_mul_f32 v[24:25], v[16:17], v[24:25]
	v_pk_mul_f32 v[16:17], v[26:27], v[164:165] op_sel_hi:[1,0]
	s_nop 0
	v_mul_f32_e32 v26, 0xbfb8aa3b, v16
	v_mul_f32_e32 v27, 0xbfb8aa3b, v17
	v_exp_f32_e32 v26, v26
	v_exp_f32_e32 v27, v27
	v_add_f32_e32 v26, 1.0, v26
	v_add_f32_e32 v27, 1.0, v27
	v_rcp_f32_e32 v26, v26
	v_rcp_f32_e32 v27, v27
	s_nop 0
	v_pk_mul_f32 v[16:17], v[16:17], v[26:27]
	s_nop 0
	v_pk_mul_f32 v[26:27], v[18:19], v[16:17]
	v_cvt_pk_bf16_f32 v16, v20, v21
	v_cvt_pk_bf16_f32 v17, v22, v23
	v_cvt_pk_bf16_f32 v18, v24, v25
	v_cvt_pk_bf16_f32 v19, v26, v27
	v_mad_i64_i32 v[20:21], s[18:19], v32, s9, v[140:141]
	global_store_dwordx4 v[20:21], v[16:19], off
	s_nop 1
	v_add_u32_e32 v16, 0xb0, v142
	v_pk_mul_f32 v[12:13], v[12:13], v[166:167] op_sel_hi:[1,0]
	s_nop 0
	v_mul_f32_e32 v17, 0xbfb8aa3b, v12
	v_exp_f32_e32 v17, v17
	v_pk_mul_f32 v[8:9], v[8:9], v[166:167] op_sel_hi:[1,0]
	v_pk_mul_f32 v[10:11], v[10:11], v[166:167] op_sel_hi:[1,0]
	v_pk_mul_f32 v[4:5], v[4:5], v[166:167] op_sel_hi:[1,0]
	v_add_f32_e32 v17, 1.0, v17
	v_rcp_f32_e32 v20, v17
	v_mul_f32_e32 v17, 0xbfb8aa3b, v13
	v_exp_f32_e32 v17, v17
	v_pk_mul_f32 v[0:1], v[0:1], v[166:167] op_sel_hi:[1,0]
	v_pk_mul_f32 v[2:3], v[2:3], v[166:167] op_sel_hi:[1,0]
	v_add_f32_e32 v17, 1.0, v17
	v_rcp_f32_e32 v21, v17
	s_nop 0
	v_pk_mul_f32 v[12:13], v[12:13], v[20:21]
	s_nop 0
	v_pk_mul_f32 v[8:9], v[8:9], v[12:13]
	v_pk_mul_f32 v[12:13], v[14:15], v[166:167] op_sel_hi:[1,0]
	s_nop 0
	v_mul_f32_e32 v14, 0xbfb8aa3b, v12
	v_mul_f32_e32 v15, 0xbfb8aa3b, v13
	v_exp_f32_e32 v14, v14
	v_exp_f32_e32 v15, v15
	v_add_f32_e32 v14, 1.0, v14
	v_add_f32_e32 v15, 1.0, v15
	v_rcp_f32_e32 v14, v14
	v_rcp_f32_e32 v15, v15
	s_nop 0
	v_pk_mul_f32 v[12:13], v[12:13], v[14:15]
	s_nop 0
	v_pk_mul_f32 v[10:11], v[10:11], v[12:13]
	v_mul_f32_e32 v12, 0xbfb8aa3b, v4
	v_mul_f32_e32 v13, 0xbfb8aa3b, v5
	v_exp_f32_e32 v12, v12
	v_exp_f32_e32 v13, v13
	v_add_f32_e32 v12, 1.0, v12
	v_add_f32_e32 v13, 1.0, v13
	v_rcp_f32_e32 v12, v12
	v_rcp_f32_e32 v13, v13
	s_nop 0
	v_pk_mul_f32 v[4:5], v[4:5], v[12:13]
	s_nop 0
	v_pk_mul_f32 v[4:5], v[0:1], v[4:5]
	v_pk_mul_f32 v[0:1], v[6:7], v[166:167] op_sel_hi:[1,0]
	s_nop 0
	v_mul_f32_e32 v6, 0xbfb8aa3b, v0
	v_mul_f32_e32 v7, 0xbfb8aa3b, v1
	v_exp_f32_e32 v6, v6
	v_exp_f32_e32 v7, v7
	v_add_f32_e32 v6, 1.0, v6
	v_add_f32_e32 v7, 1.0, v7
	v_rcp_f32_e32 v6, v6
	v_rcp_f32_e32 v7, v7
	s_nop 0
	v_pk_mul_f32 v[0:1], v[0:1], v[6:7]
	s_nop 0
	v_pk_mul_f32 v[6:7], v[2:3], v[0:1]
	v_cvt_pk_bf16_f32 v2, v4, v5
	v_mad_i64_i32 v[4:5], s[18:19], v16, s9, v[140:141]
	v_cvt_pk_bf16_f32 v0, v8, v9
	v_cvt_pk_bf16_f32 v1, v10, v11
	v_cvt_pk_bf16_f32 v3, v6, v7
	s_mov_b64 s[18:19], -1
	global_store_dwordx4 v[4:5], v[0:3], off
	s_cbranch_vccnz .LBB0_614
	s_andn2_b64 vcc, exec, s[0:1]
	s_cbranch_vccnz .LBB0_613
	s_barrier
	s_branch .LBB0_613
